# DIFF attention: all 8 V fragments of a 32-key block prefetched from LDS into dedicated registers at step start (no ds_read->lgkmcnt(0)->MFMA chains), on top of v4
# speedup vs baseline: 1.0124x; 1.0124x over previous
.LBB0_681:
	v_add3_u32 v1, s21, v209, v213
	ds_read_b128 v[6:9], v1
	ds_read_b128 v[10:13], v1 offset:32
	ds_read_b128 v[96:99], v1 offset:64
	ds_read_b128 v[2:5], v1 offset:96
	s_mulk_i32 s31, 0x4800
	v_add_u32_e32 v132, s31, v223
	ds_read_b128 v[100:103], v132 offset:18496
	ds_read_b128 v[104:107], v132 offset:18528
	ds_read_b128 v[108:111], v132 offset:23104
	ds_read_b128 v[112:115], v132 offset:23136
	ds_read_b128 v[116:119], v132 offset:27712
	ds_read_b128 v[120:123], v132 offset:27744
	ds_read_b128 v[124:127], v132 offset:32320
	ds_read_b128 v[128:131], v132 offset:32352
	v_max_f32_e32 v1, v17, v17
	s_waitcnt lgkmcnt(11)
	v_mfma_f32_32x32x16_bf16 v[160:175], v[6:9], v[176:179], 0
	v_sub_f32_e32 v7, v16, v217
	v_exp_f32_e32 v7, v7
	v_sub_f32_e32 v9, v17, v217
	v_exp_f32_e32 v9, v9
	v_max_f32_e32 v14, v16, v16
	v_add_f32_e32 v8, 0, v7
	v_max_f32_e32 v1, v14, v1
	s_waitcnt lgkmcnt(10)
	v_mfma_f32_32x32x16_bf16 v[160:175], v[10:13], v[180:183], v[160:175]
	v_sub_f32_e32 v10, v18, v217
	v_exp_f32_e32 v11, v10
	v_sub_f32_e32 v10, v19, v217
	v_exp_f32_e32 v12, v10
	v_sub_f32_e32 v10, v20, v217
	v_exp_f32_e32 v13, v10
	v_sub_f32_e32 v10, v21, v217
	v_add_f32_e32 v8, v9, v8
	v_exp_f32_e32 v14, v10
	v_sub_f32_e32 v10, v22, v217
	v_add_f32_e32 v8, v11, v8
	v_exp_f32_e32 v15, v10
	v_sub_f32_e32 v10, v23, v217
	v_max3_f32 v1, v1, v18, v19
	v_add_f32_e32 v8, v12, v8
	v_exp_f32_e32 v16, v10
	v_sub_f32_e32 v10, v24, v217
	v_max3_f32 v1, v1, v20, v21
	v_add_f32_e32 v8, v13, v8
	v_exp_f32_e32 v17, v10
	v_sub_f32_e32 v10, v25, v217
	v_max3_f32 v1, v1, v22, v23
	v_add_f32_e32 v8, v14, v8
	v_exp_f32_e32 v18, v10
	v_sub_f32_e32 v10, v26, v217
	v_max3_f32 v1, v1, v24, v25
	v_add_f32_e32 v8, v15, v8
	v_exp_f32_e32 v19, v10
	v_sub_f32_e32 v10, v27, v217
	v_max3_f32 v1, v1, v26, v27
	v_add_f32_e32 v8, v16, v8
	v_exp_f32_e32 v20, v10
	v_sub_f32_e32 v10, v28, v217
	v_max3_f32 v1, v1, v28, v29
	v_add_f32_e32 v8, v17, v8
	v_exp_f32_e32 v21, v10
	v_sub_f32_e32 v10, v29, v217
	v_max3_f32 v1, v1, v30, v31
	v_add_f32_e32 v8, v18, v8
	v_exp_f32_e32 v22, v10
	v_sub_f32_e32 v10, v30, v217
	ds_bpermute_b32 v6, v247, v1
	v_add_f32_e32 v8, v19, v8
	v_exp_f32_e32 v23, v10
	v_sub_f32_e32 v10, v31, v217
	v_add_f32_e32 v8, v20, v8
	v_exp_f32_e32 v24, v10
	v_add_f32_e32 v8, v21, v8
	v_add_f32_e32 v8, v22, v8
	v_add_f32_e32 v8, v23, v8
	v_add_f32_e32 v8, v24, v8
	s_waitcnt lgkmcnt(0)
	v_max_f32_e32 v6, v6, v6
	v_max_f32_e32 v210, v1, v6
	v_add_f32_e32 v1, v216, v8
	v_cvt_pk_bf16_f32 v8, v21, v22
	v_cvt_pk_bf16_f32 v10, v7, v9
	v_cvt_pk_bf16_f32 v11, v11, v12
	v_cvt_pk_bf16_f32 v12, v13, v14
	v_cvt_pk_bf16_f32 v13, v15, v16
	v_cvt_pk_bf16_f32 v6, v17, v18
	v_cvt_pk_bf16_f32 v7, v19, v20
	v_mfma_f32_32x32x16_bf16 v[160:175], v[96:99], v[184:187], v[160:175]
	v_cvt_pk_bf16_f32 v9, v23, v24
	v_mfma_f32_32x32x16_bf16 v[32:47], v[100:103], v[10:13], v[32:47]
	v_mfma_f32_32x32x16_bf16 v[48:63], v[108:111], v[10:13], v[48:63]
	v_mfma_f32_32x32x16_bf16 v[48:63], v[112:115], v[6:9], v[48:63]
	v_mfma_f32_32x32x16_bf16 v[64:79], v[116:119], v[10:13], v[64:79]
	v_mfma_f32_32x32x16_bf16 v[64:79], v[120:123], v[6:9], v[64:79]
	v_mfma_f32_32x32x16_bf16 v[80:95], v[124:127], v[10:13], v[80:95]
	v_mfma_f32_32x32x16_bf16 v[32:47], v[104:107], v[6:9], v[32:47]
	v_mfma_f32_32x32x16_bf16 v[80:95], v[128:131], v[6:9], v[80:95]
	v_mfma_f32_32x32x16_bf16 v[16:31], v[2:5], v[188:191], v[160:175]
	v_sub_f32_e32 v2, v210, v217
	v_cmp_lt_f32_e32 vcc, s2, v2
	s_cbranch_vccz .LBB0_698
	v_max_f32_e32 v2, v2, v2
	v_max_f32_e32 v3, 0, v2
	v_exp_f32_e64 v2, -v3
	v_add_f32_e32 v6, v217, v3
	v_mul_f32_e32 v1, v2, v1
	s_nop 3
	v_pk_mul_f32 v[46:47], v[46:47], v[2:3] op_sel_hi:[1,0]
	v_pk_mul_f32 v[44:45], v[44:45], v[2:3] op_sel_hi:[1,0]
	v_pk_mul_f32 v[42:43], v[42:43], v[2:3] op_sel_hi:[1,0]
	v_pk_mul_f32 v[40:41], v[40:41], v[2:3] op_sel_hi:[1,0]
	v_pk_mul_f32 v[38:39], v[38:39], v[2:3] op_sel_hi:[1,0]
	v_pk_mul_f32 v[36:37], v[36:37], v[2:3] op_sel_hi:[1,0]
	v_pk_mul_f32 v[34:35], v[34:35], v[2:3] op_sel_hi:[1,0]
	v_pk_mul_f32 v[32:33], v[32:33], v[2:3] op_sel_hi:[1,0]
	v_pk_mul_f32 v[62:63], v[62:63], v[2:3] op_sel_hi:[1,0]
	v_pk_mul_f32 v[60:61], v[60:61], v[2:3] op_sel_hi:[1,0]
	v_pk_mul_f32 v[58:59], v[58:59], v[2:3] op_sel_hi:[1,0]
	v_pk_mul_f32 v[56:57], v[56:57], v[2:3] op_sel_hi:[1,0]
	v_pk_mul_f32 v[54:55], v[54:55], v[2:3] op_sel_hi:[1,0]
	v_pk_mul_f32 v[52:53], v[52:53], v[2:3] op_sel_hi:[1,0]
	v_pk_mul_f32 v[50:51], v[50:51], v[2:3] op_sel_hi:[1,0]
	v_pk_mul_f32 v[48:49], v[48:49], v[2:3] op_sel_hi:[1,0]
	v_pk_mul_f32 v[78:79], v[2:3], v[78:79] op_sel_hi:[0,1]
	v_pk_mul_f32 v[76:77], v[2:3], v[76:77] op_sel_hi:[0,1]
	v_pk_mul_f32 v[74:75], v[2:3], v[74:75] op_sel_hi:[0,1]
	v_pk_mul_f32 v[72:73], v[2:3], v[72:73] op_sel_hi:[0,1]
	v_pk_mul_f32 v[70:71], v[2:3], v[70:71] op_sel_hi:[0,1]
	v_pk_mul_f32 v[68:69], v[2:3], v[68:69] op_sel_hi:[0,1]
	v_pk_mul_f32 v[66:67], v[2:3], v[66:67] op_sel_hi:[0,1]
	v_pk_mul_f32 v[64:65], v[2:3], v[64:65] op_sel_hi:[0,1]
	v_pk_mul_f32 v[94:95], v[2:3], v[94:95] op_sel_hi:[0,1]
	v_pk_mul_f32 v[92:93], v[2:3], v[92:93] op_sel_hi:[0,1]
	v_pk_mul_f32 v[90:91], v[2:3], v[90:91] op_sel_hi:[0,1]
	v_pk_mul_f32 v[88:89], v[2:3], v[88:89] op_sel_hi:[0,1]
	v_pk_mul_f32 v[86:87], v[2:3], v[86:87] op_sel_hi:[0,1]
	v_pk_mul_f32 v[84:85], v[2:3], v[84:85] op_sel_hi:[0,1]
	v_pk_mul_f32 v[82:83], v[2:3], v[82:83] op_sel_hi:[0,1]
	v_pk_mul_f32 v[80:81], v[2:3], v[80:81] op_sel_hi:[0,1]
	s_cbranch_execz .LBB0_685
	s_branch .LBB0_686

.LBB0_694:
	v_add3_u32 v119, s21, v209, v213
	ds_read_b128 v[2:5], v119 offset:4608
	ds_read_b128 v[10:13], v119 offset:4640
	s_mul_i32 s21, s19, 0x4800
	v_add_u32_e32 v132, s21, v223
	ds_read_b128 v[124:127], v132 offset:18432
	ds_read_b128 v[128:131], v132 offset:18464
	ds_read_b128 v[134:137], v132 offset:23040
	ds_read_b128 v[138:141], v132 offset:23072
	ds_read_b128 v[142:145], v132 offset:27648
	ds_read_b128 v[146:149], v132 offset:27680
	ds_read_b128 v[150:153], v132 offset:32256
	ds_read_b128 v[154:157], v132 offset:32288
	v_sub_f32_e32 v113, v22, v6
	v_sub_f32_e32 v14, v19, v6
	v_sub_f32_e32 v114, v23, v6
	v_sub_f32_e32 v15, v20, v6
	v_sub_f32_e32 v115, v24, v6
	s_waitcnt lgkmcnt(9)
	v_mfma_f32_32x32x16_bf16 v[96:111], v[2:5], v[176:179], 0
	ds_read_b128 v[2:5], v119 offset:4672
	v_sub_f32_e32 v7, v16, v6
	v_sub_f32_e32 v8, v17, v6
	v_sub_f32_e32 v9, v18, v6
	v_sub_f32_e32 v112, v21, v6
	v_exp_f32_e32 v7, v7
	s_waitcnt lgkmcnt(9)
	v_mfma_f32_32x32x16_bf16 v[96:111], v[10:13], v[180:183], v[96:111]
	v_exp_f32_e32 v13, v113
	v_exp_f32_e32 v10, v14
	v_exp_f32_e32 v14, v114
	v_exp_f32_e32 v11, v15
	v_exp_f32_e32 v15, v115
	v_exp_f32_e32 v8, v8
	v_exp_f32_e32 v9, v9
	s_waitcnt lgkmcnt(0)
	v_mfma_f32_32x32x16_bf16 v[96:111], v[2:5], v[184:187], v[96:111]
	v_sub_f32_e32 v2, v26, v6
	v_exp_f32_e32 v113, v2
	v_sub_f32_e32 v2, v27, v6
	v_exp_f32_e32 v114, v2
	v_sub_f32_e32 v2, v28, v6
	v_exp_f32_e32 v115, v2
	v_exp_f32_e32 v12, v112
	v_cvt_pk_bf16_f32 v120, v7, v8
	v_cvt_pk_bf16_f32 v121, v9, v10
	v_cvt_pk_bf16_f32 v123, v13, v14
	v_cvt_pk_bf16_f32 v122, v11, v12
	v_sub_f32_e32 v116, v25, v6
	v_exp_f32_e32 v112, v116
	v_mfma_f32_32x32x16_bf16 v[32:47], v[124:127], v[120:123], v[32:47]
	ds_read_b128 v[124:127], v119 offset:4704
	v_sub_f32_e32 v116, v29, v6
	v_sub_f32_e32 v117, v30, v6
	v_sub_f32_e32 v2, v31, v6
	v_exp_f32_e32 v116, v116
	v_exp_f32_e32 v117, v117
	v_exp_f32_e32 v118, v2
	v_cvt_pk_bf16_f32 v2, v15, v112
	v_cvt_pk_bf16_f32 v3, v113, v114
	v_cvt_pk_bf16_f32 v4, v115, v116
	v_cvt_pk_bf16_f32 v5, v117, v118
	v_max_f32_e32 v17, v17, v17
	v_max_f32_e32 v16, v16, v16
	v_mfma_f32_32x32x16_bf16 v[32:47], v[128:131], v[2:5], v[32:47]
	v_max_f32_e32 v16, v16, v17
	v_max3_f32 v16, v16, v18, v19
	v_max3_f32 v16, v16, v20, v21
	v_max3_f32 v16, v16, v22, v23
	v_max3_f32 v20, v16, v24, v25
	v_mfma_f32_32x32x16_bf16 v[48:63], v[134:137], v[120:123], v[48:63]
	v_max3_f32 v20, v20, v26, v27
	v_max3_f32 v20, v20, v28, v29
	v_max3_f32 v20, v20, v30, v31
	ds_bpermute_b32 v21, v247, v20
	s_andn2_b64 vcc, exec, s[92:93]
	v_mfma_f32_32x32x16_bf16 v[48:63], v[138:141], v[2:5], v[48:63]
	v_mfma_f32_32x32x16_bf16 v[64:79], v[142:145], v[120:123], v[64:79]
	v_mfma_f32_32x32x16_bf16 v[80:95], v[150:153], v[120:123], v[80:95]
	v_mfma_f32_32x32x16_bf16 v[64:79], v[146:149], v[2:5], v[64:79]
	v_mfma_f32_32x32x16_bf16 v[80:95], v[154:157], v[2:5], v[80:95]
	s_waitcnt lgkmcnt(0)
	v_max_f32_e32 v2, v21, v21
	v_max_f32_e32 v2, v20, v2
	v_sub_f32_e32 v2, v2, v6
	v_mfma_f32_32x32x16_bf16 v[16:31], v[124:127], v[188:191], v[96:111]
	s_cbranch_vccnz .LBB0_697
	v_cmp_lt_f32_e32 vcc, s2, v2
	s_cbranch_vccz .LBB0_699
	v_max_f32_e32 v2, v2, v2
	v_max_f32_e32 v2, 0, v2
